# stack14: + attention tile loop waits only for the staged register set
# speedup vs baseline: 1.0042x; 1.0026x over previous
;     ...
;     auto compute = [&](int buf, int t) {
;         const LAS bf16* Ks = (const LAS bf16*)(lds + koff(buf)); const LAS bf16* VT = (const LAS bf16*)(lds + voff(buf));
;         bf16x8 kf[2][4]; float bias[2][2][4];
; #pragma unroll
;         for (int kb = 0; kb < 2; ++kb)
; #pragma unroll
;             for (int ks = 0; ks < 4; ++ks) kf[kb][ks] = *(const LAS bf16x8*)(Ks + (32 * kh + 16 * kb + fr) * QP + 32 * ks + 8 * fq);
;         if (MODE == 0) { const LAS float* bp = BT + (2047 - 16 - (q0 + 32 * rp + fr - t * 64 - 32 * kh - 4 * fq));
; #pragma unroll
;                 for (int kb = 0; kb < 2; ++kb)
; #pragma unroll
;                     for (int i = 0; i < 4; ++i) bias[0][kb][i] = bp[16 * (kb + 1) + i]; }
;         __builtin_amdgcn_sched_barrier(0);
;         f32x4 s[2][2];
; #pragma unroll
;         for (int rb = 0; rb < 2; ++rb)
; #pragma unroll
;             for (int kb = 0; kb < 2; ++kb) s[rb][kb] = (f32x4){0.f, 0.f, 0.f, 0.f};
;         bf16x8 pf[2];
;         auto smax = [&](int rb) {
;             if (MODE == 0) { s[rb][0] = s[rb][0] + (f32x4){bias[rb][0][0], bias[rb][0][1], bias[rb][0][2], bias[rb][0][3]}; s[rb][1] = s[rb][1] + (f32x4){bias[rb][1][0], bias[rb][1][1], bias[rb][1][2], bias[rb][1][3]}; }
;             else { s[rb][0] = s[rb][0] - bref; s[rb][1] = s[rb][1] - bref; }
;             float ps = 0.f;
; #pragma unroll
;             for (int kb = 0; kb < 2; ++kb)
; #pragma unroll
;                 for (int i = 0; i < 4; ++i) { s[rb][kb][i] = __builtin_amdgcn_exp2f(s[rb][kb][i]); ps += s[rb][kb][i]; }
;             lrun[rb] += ps;
;             u32x4 pw; pw.x = pk2(s[rb][0][0], s[rb][0][1]); pw.y = pk2(s[rb][0][2], s[rb][0][3]); pw.z = pk2(s[rb][1][0], s[rb][1][1]); pw.w = pk2(s[rb][1][2], s[rb][1][3]);
;             pf[rb] = __builtin_bit_cast(bf16x8, pw); };
; #pragma unroll
;         for (int ks = 0; ks < 4; ++ks)
; #pragma unroll
;             for (int kb = 0; kb < 2; ++kb) MMA16(kf[kb][ks], qf[0][ks], s[0][kb]);
;         __builtin_amdgcn_sched_barrier(0);
;         bf16x8 vf[8];
; #pragma unroll
;         for (int db = 0; db < 8; ++db) vf[db] = *(const LAS bf16x8*)(VT + (16 * db + fr) * VPA + 32 * kh + 8 * fq);
;         if (MODE == 0) { const LAS float* bp = BT + (2047 - 16 - (q0 + 32 * rp + fr - t * 64 - 32 * kh - 4 * fq));
; #pragma unroll
;             for (int kb = 0; kb < 2; ++kb)
; #pragma unroll
.LBB0_122:
	s_add_i32 s58, s63, -1
	s_cmp_gt_i32 s63, 0
	s_cselect_b32 s58, s58, 2
	s_add_i32 s59, s41, -3
	s_cmp_ge_u32 s59, s40
	s_cbranch_scc1 .LBB0_125
	s_mul_i32 s68, s58, 0x9800
	s_add_i32 s68, s68, 0
	v_add3_u32 v128, s68, v149, v152
	s_waitcnt vmcnt(7)
	ds_write_b128 v128, v[32:35]
	s_waitcnt vmcnt(6)
	ds_write_b128 v128, v[36:39] offset:128
	v_add3_u32 v128, s68, v157, v148
	s_add_i32 s68, s41, -1
	s_cmp_ge_u32 s68, s40
	s_waitcnt vmcnt(4)
	ds_write_b128 v128, v[44:47] offset:18432
	ds_write_b128 v128, v[40:43] offset:18448
	s_cbranch_scc1 .LBB0_125
	global_load_dwordx4 v[32:35], v[160:161], off
	global_load_dwordx4 v[36:39], v[160:161], off offset:128
	global_load_dwordx4 v[40:43], v[158:159], off offset:16
	global_load_dwordx4 v[44:47], v[158:159], off
.LBB0_125:
	s_mul_i32 s78, s63, 0x9800
	s_add_i32 s79, s78, 0
	v_add_u32_e32 v171, s79, v165
	v_add_u32_e32 v182, v171, v167
	ds_read_b128 v[128:131], v182
	ds_read_b128 v[132:135], v182 offset:64
	ds_read_b128 v[136:139], v182 offset:128
	ds_read_b128 v[140:143], v182 offset:192
	ds_read_b128 v[144:147], v182 offset:4608
	ds_read_b128 v[172:175], v182 offset:4672
	ds_read_b128 v[192:195], v182 offset:4736
	ds_read_b128 v[196:199], v182 offset:4800
	ds_read2_b32 v[182:183], v170 offset0:16 offset1:17
	ds_read2_b32 v[184:185], v170 offset0:18 offset1:19
	ds_read2_b32 v[188:189], v170 offset0:32 offset1:33
	ds_read2_b32 v[190:191], v170 offset0:34 offset1:35
	s_waitcnt lgkmcnt(11)
	v_mfma_f32_16x16x32_bf16 v[200:203], v[128:131], v[76:79], 0
	s_waitcnt lgkmcnt(7)
	v_mfma_f32_16x16x32_bf16 v[204:207], v[144:147], v[76:79], 0
	v_mfma_f32_16x16x32_bf16 v[200:203], v[132:135], v[80:83], v[200:203]
	s_waitcnt lgkmcnt(6)
	v_mfma_f32_16x16x32_bf16 v[204:207], v[172:175], v[80:83], v[204:207]
	v_mfma_f32_16x16x32_bf16 v[200:203], v[136:139], v[84:87], v[200:203]
	s_waitcnt lgkmcnt(5)
	v_mfma_f32_16x16x32_bf16 v[204:207], v[192:195], v[84:87], v[204:207]
	v_mfma_f32_16x16x32_bf16 v[200:203], v[140:143], v[88:91], v[200:203]
	s_waitcnt lgkmcnt(4)
	v_mfma_f32_16x16x32_bf16 v[204:207], v[196:199], v[88:91], v[204:207]
	v_mfma_f32_16x16x32_bf16 v[128:131], v[128:131], v[92:95], 0
	ds_read2_b32 v[212:213], v170 offset1:1
	v_add3_u32 v171, v171, v168, v169
	s_waitcnt lgkmcnt(3)
	s_nop 1
	v_pk_add_f32 v[184:185], v[184:185], v[202:203]
	v_pk_add_f32 v[182:183], v[182:183], v[200:201]
	s_waitcnt lgkmcnt(1)
	v_pk_add_f32 v[190:191], v[190:191], v[206:207]
	v_mfma_f32_16x16x32_bf16 v[144:147], v[144:147], v[92:95], 0
	ds_read_b128 v[200:203], v171 offset:36352
	v_pk_add_f32 v[188:189], v[188:189], v[204:205]
	ds_read2_b32 v[224:225], v170 offset0:16 offset1:17
	v_mfma_f32_16x16x32_bf16 v[128:131], v[132:135], v[96:99], v[128:131]
	ds_read_b128 v[204:207], v171 offset:18432
	ds_read2_b32 v[226:227], v170 offset0:18 offset1:19
	ds_read_b128 v[216:219], v171 offset:33792
	v_mfma_f32_16x16x32_bf16 v[132:135], v[172:175], v[96:99], v[144:147]
	s_nop 2
	ds_read_b128 v[144:147], v171 offset:20992
	v_mfma_f32_16x16x32_bf16 v[128:131], v[136:139], v[100:103], v[128:131]
	ds_read_b128 v[172:175], v171 offset:23552
	v_exp_f32_e32 v139, v184
	v_exp_f32_e32 v137, v185
	v_mfma_f32_16x16x32_bf16 v[132:135], v[192:195], v[100:103], v[132:135]
	ds_read_b128 v[192:195], v171 offset:26112
	v_mfma_f32_16x16x32_bf16 v[128:131], v[140:143], v[104:107], v[128:131]
	ds_read_b128 v[208:211], v171 offset:28672
	v_exp_f32_e32 v143, v182
	v_exp_f32_e32 v141, v183
	s_waitcnt lgkmcnt(9)
	s_nop 3
	v_pk_add_f32 v[220:221], v[212:213], v[128:129]
	v_mfma_f32_16x16x32_bf16 v[196:199], v[196:199], v[104:107], v[132:135]
	ds_read2_b32 v[128:129], v170 offset0:2 offset1:3
	ds_read_b128 v[212:215], v171 offset:31232
	v_exp_f32_e32 v142, v220
	v_exp_f32_e32 v135, v188
	v_exp_f32_e32 v133, v189
	s_waitcnt lgkmcnt(1)
	v_pk_add_f32 v[222:223], v[128:129], v[130:131]
	s_nop 0
	v_pk_add_f32 v[182:183], v[226:227], v[198:199]
	v_pk_add_f32 v[184:185], v[224:225], v[196:197]
	v_exp_f32_e32 v131, v190
	v_exp_f32_e32 v129, v191
	v_exp_f32_e32 v140, v221
	v_exp_f32_e32 v138, v222
	v_exp_f32_e32 v136, v223
	v_exp_f32_e32 v134, v184
	v_exp_f32_e32 v132, v185
	v_exp_f32_e32 v130, v182
	v_exp_f32_e32 v128, v183
	v_cvt_pk_bf16_f32 v196, v143, v141
	v_cvt_pk_bf16_f32 v197, v139, v137
	v_cvt_pk_bf16_f32 v198, v135, v133
	v_cvt_pk_bf16_f32 v199, v131, v129
	s_nop 0
	v_mfma_f32_16x16x32_bf16 v[124:127], v[204:207], v[196:199], v[124:127]
	v_mfma_f32_16x16x32_bf16 v[120:123], v[144:147], v[196:199], v[120:123]
	v_mfma_f32_16x16x32_bf16 v[116:119], v[172:175], v[196:199], v[116:119]
	v_mfma_f32_16x16x32_bf16 v[112:115], v[192:195], v[196:199], v[112:115]
	v_mfma_f32_16x16x32_bf16 v[108:111], v[208:211], v[196:199], v[108:111]
	s_waitcnt lgkmcnt(0)
	v_mfma_f32_16x16x32_bf16 v[72:75], v[212:215], v[196:199], v[72:75]
	v_mfma_f32_16x16x32_bf16 v[68:71], v[216:219], v[196:199], v[68:71]
	v_mfma_f32_16x16x32_bf16 v[64:67], v[200:203], v[196:199], v[64:67]
	v_cvt_pk_bf16_f32 v196, v142, v140
	v_cvt_pk_bf16_f32 v197, v138, v136
	v_cvt_pk_bf16_f32 v198, v134, v132
	v_cvt_pk_bf16_f32 v199, v130, v128
	s_nop 0
	v_mfma_f32_16x16x32_bf16 v[28:31], v[204:207], v[196:199], v[28:31]
	v_mfma_f32_16x16x32_bf16 v[24:27], v[144:147], v[196:199], v[24:27]
	v_mfma_f32_16x16x32_bf16 v[20:23], v[172:175], v[196:199], v[20:23]
	v_mfma_f32_16x16x32_bf16 v[16:19], v[192:195], v[196:199], v[16:19]
	v_mfma_f32_16x16x32_bf16 v[12:15], v[208:211], v[196:199], v[12:15]
	v_mfma_f32_16x16x32_bf16 v[8:11], v[212:215], v[196:199], v[8:11]
	v_mfma_f32_16x16x32_bf16 v[4:7], v[216:219], v[196:199], v[4:7]
	v_mfma_f32_16x16x32_bf16 v[0:3], v[200:203], v[196:199], v[0:3]
	s_add_i32 s68, s41, -2
	s_cmp_ge_u32 s68, s40
	s_barrier
	s_cbranch_scc1 .LBB0_121
	v_add3_u32 v144, s79, v149, v152
	s_add_i32 s68, s41, -1
	s_cmp_ge_u32 s68, s40
	s_cbranch_scc1 .Lattn_b_short
	s_waitcnt vmcnt(7)
	ds_write_b128 v144, v[48:51]
	s_waitcnt vmcnt(6)
	ds_write_b128 v144, v[52:55] offset:128
	v_add3_u32 v144, s79, v157, v148
	s_waitcnt vmcnt(4)
	s_branch .Lattn_b_join
.Lattn_b_short:
	s_waitcnt vmcnt(3)
	ds_write_b128 v144, v[48:51]
	s_waitcnt vmcnt(2)
	ds_write_b128 v144, v[52:55] offset:128
	v_add3_u32 v144, s79, v157, v148
	s_waitcnt vmcnt(0)
.Lattn_b_join:
	s_cmp_ge_u32 s41, s40
	ds_write_b128 v144, v[60:63] offset:18432
	ds_write_b128 v144, v[56:59] offset:18448
	s_cbranch_scc1 .LBB0_121
	v_add_co_u32_e32 v52, vcc, 0xc0000, v160
	s_nop 1
	v_addc_co_u32_e32 v53, vcc, 0, v161, vcc
	global_load_dwordx4 v[48:51], v[52:53], off
	s_nop 0
	global_load_dwordx4 v[52:55], v[52:53], off offset:128
	s_nop 0
	global_load_dwordx4 v[56:59], v[158:159], off offset:144
	global_load_dwordx4 v[60:63], v[158:159], off offset:128
	s_branch .LBB0_121
